# Fourier stage-1 items: all 16 DFT-table fragment loads issued up front with counted waits (was 8 serialized round trips)
# baseline (speedup 1.0000x reference)
.LBB0_127:
	s_or_b64 exec, exec, s[14:15]
	v_or_b32_e32 v11, 1, v10
	s_waitcnt vmcnt(0)
	v_lshrrev_b32_e32 v4, 16, v4
	v_cmp_lt_u32_e32 vcc, 32, v11
	s_and_saveexec_b64 s[14:15], vcc
	s_xor_b64 s[14:15], exec, s[14:15]
	ds_write_b16 v9, v4 offset:66
	v_xor_b32_e32 v4, 0xffff8000, v4
	s_or_saveexec_b64 s[14:15], s[14:15]
	v_mov_b32_e32 v12, 0xa0
	s_xor_b64 exec, exec, s[14:15]
	v_mov_b32_e32 v12, 64
	ds_write_b16 v9, v4 offset:2
	s_or_b64 exec, exec, s[14:15]
	v_sub_u32_e32 v11, v12, v11
	v_lshl_add_u32 v11, v11, 1, v8
	ds_write_b16 v11, v4
	v_or_b32_e32 v4, 2, v10
	v_cmp_lt_u32_e32 vcc, 32, v4
	s_and_saveexec_b64 s[14:15], vcc
	s_xor_b64 s[14:15], exec, s[14:15]
	v_xor_b32_e32 v11, 0xffff8000, v5
	ds_write_b16 v9, v5 offset:68
	s_or_saveexec_b64 s[14:15], s[14:15]
	v_mov_b32_e32 v12, 0xa0
	s_xor_b64 exec, exec, s[14:15]
	v_mov_b32_e32 v12, 64
	v_mov_b32_e32 v11, v5
	ds_write_b16 v9, v5 offset:4
	s_or_b64 exec, exec, s[14:15]
	v_sub_u32_e32 v4, v12, v4
	v_lshl_add_u32 v4, v4, 1, v8
	ds_write_b16 v4, v11
	v_lshrrev_b32_e32 v4, 16, v5
	v_or_b32_e32 v5, 3, v10
	v_cmp_lt_u32_e32 vcc, 32, v5
	s_and_saveexec_b64 s[14:15], vcc
	s_xor_b64 s[14:15], exec, s[14:15]
	ds_write_b16 v9, v4 offset:70
	v_xor_b32_e32 v4, 0xffff8000, v4
	s_or_saveexec_b64 s[14:15], s[14:15]
	v_mov_b32_e32 v11, 0xa0
	s_xor_b64 exec, exec, s[14:15]
	v_mov_b32_e32 v11, 64
	ds_write_b16 v9, v4 offset:6
	s_or_b64 exec, exec, s[14:15]
	v_sub_u32_e32 v5, v11, v5
	v_lshl_add_u32 v5, v5, 1, v8
	ds_write_b16 v5, v4
	v_or_b32_e32 v4, 4, v10
	v_cmp_lt_u32_e32 vcc, 32, v4
	s_and_saveexec_b64 s[14:15], vcc
	s_xor_b64 s[14:15], exec, s[14:15]
	v_xor_b32_e32 v5, 0xffff8000, v6
	ds_write_b16 v9, v6 offset:72
	s_or_saveexec_b64 s[14:15], s[14:15]
	v_mov_b32_e32 v11, 0xa0
	s_xor_b64 exec, exec, s[14:15]
	v_mov_b32_e32 v11, 64
	v_mov_b32_e32 v5, v6
	ds_write_b16 v9, v6 offset:8
	s_or_b64 exec, exec, s[14:15]
	v_sub_u32_e32 v4, v11, v4
	v_lshl_add_u32 v4, v4, 1, v8
	ds_write_b16 v4, v5
	v_or_b32_e32 v5, 5, v10
	v_lshrrev_b32_e32 v4, 16, v6
	v_cmp_lt_u32_e32 vcc, 32, v5
	s_and_saveexec_b64 s[14:15], vcc
	s_xor_b64 s[14:15], exec, s[14:15]
	ds_write_b16 v9, v4 offset:74
	v_xor_b32_e32 v4, 0xffff8000, v4
	s_or_saveexec_b64 s[14:15], s[14:15]
	v_mov_b32_e32 v6, 0xa0
	s_xor_b64 exec, exec, s[14:15]
	v_mov_b32_e32 v6, 64
	ds_write_b16 v9, v4 offset:10
	s_or_b64 exec, exec, s[14:15]
	v_sub_u32_e32 v5, v6, v5
	v_lshl_add_u32 v5, v5, 1, v8
	ds_write_b16 v5, v4
	v_or_b32_e32 v4, 6, v10
	v_cmp_lt_u32_e32 vcc, 32, v4
	s_and_saveexec_b64 s[14:15], vcc
	s_xor_b64 s[14:15], exec, s[14:15]
	v_xor_b32_e32 v5, 0xffff8000, v7
	ds_write_b16 v9, v7 offset:76
	s_or_saveexec_b64 s[14:15], s[14:15]
	v_mov_b32_e32 v6, 0xa0
	s_xor_b64 exec, exec, s[14:15]
	v_mov_b32_e32 v6, 64
	v_mov_b32_e32 v5, v7
	ds_write_b16 v9, v7 offset:12
	s_or_b64 exec, exec, s[14:15]
	v_sub_u32_e32 v4, v6, v4
	v_lshl_add_u32 v4, v4, 1, v8
	ds_write_b16 v4, v5
	v_or_b32_e32 v5, 7, v10
	v_lshrrev_b32_e32 v4, 16, v7
	v_cmp_lt_u32_e32 vcc, 32, v5
	s_and_saveexec_b64 s[14:15], vcc
	s_xor_b64 s[14:15], exec, s[14:15]
	ds_write_b16 v9, v4 offset:78
	v_xor_b32_e32 v4, 0xffff8000, v4
	s_or_saveexec_b64 s[14:15], s[14:15]
	v_mov_b32_e32 v6, 0xa0
	s_xor_b64 exec, exec, s[14:15]
	v_mov_b32_e32 v6, 64
	ds_write_b16 v9, v4 offset:14
	s_or_b64 exec, exec, s[14:15]
	v_sub_u32_e32 v5, v6, v5
	v_lshl_add_u32 v5, v5, 1, v8
	ds_write_b16 v5, v4
	v_or_b32_e32 v4, 8, v10
	v_cmp_lt_u32_e32 vcc, 32, v4
	s_and_saveexec_b64 s[14:15], vcc
	s_xor_b64 s[14:15], exec, s[14:15]
	v_xor_b32_e32 v5, 0xffff8000, v0
	ds_write_b16 v9, v0 offset:80
	s_or_saveexec_b64 s[14:15], s[14:15]
	v_mov_b32_e32 v6, 0xa0
	s_xor_b64 exec, exec, s[14:15]
	v_mov_b32_e32 v6, 64
	v_mov_b32_e32 v5, v0
	ds_write_b16 v9, v0 offset:16
	s_or_b64 exec, exec, s[14:15]
	v_sub_u32_e32 v4, v6, v4
	v_lshl_add_u32 v4, v4, 1, v8
	ds_write_b16 v4, v5
	v_or_b32_e32 v4, 9, v10
	v_lshrrev_b32_e32 v0, 16, v0
	v_cmp_lt_u32_e32 vcc, 32, v4
	s_and_saveexec_b64 s[14:15], vcc
	s_xor_b64 s[14:15], exec, s[14:15]
	ds_write_b16 v9, v0 offset:82
	v_xor_b32_e32 v0, 0xffff8000, v0
	s_or_saveexec_b64 s[14:15], s[14:15]
	v_mov_b32_e32 v5, 0xa0
	s_xor_b64 exec, exec, s[14:15]
	v_mov_b32_e32 v5, 64
	ds_write_b16 v9, v0 offset:18
	s_or_b64 exec, exec, s[14:15]
	v_sub_u32_e32 v4, v5, v4
	v_lshl_add_u32 v4, v4, 1, v8
	ds_write_b16 v4, v0
	v_or_b32_e32 v0, 10, v10
	v_cmp_lt_u32_e32 vcc, 32, v0
	s_and_saveexec_b64 s[14:15], vcc
	s_xor_b64 s[14:15], exec, s[14:15]
	v_xor_b32_e32 v4, 0xffff8000, v1
	ds_write_b16 v9, v1 offset:84
	s_or_saveexec_b64 s[14:15], s[14:15]
	v_mov_b32_e32 v5, 0xa0
	s_xor_b64 exec, exec, s[14:15]
	v_mov_b32_e32 v5, 64
	v_mov_b32_e32 v4, v1
	ds_write_b16 v9, v1 offset:20
	s_or_b64 exec, exec, s[14:15]
	v_sub_u32_e32 v0, v5, v0
	v_lshl_add_u32 v0, v0, 1, v8
	ds_write_b16 v0, v4
	v_lshrrev_b32_e32 v0, 16, v1
	v_or_b32_e32 v1, 11, v10
	v_cmp_lt_u32_e32 vcc, 32, v1
	s_and_saveexec_b64 s[14:15], vcc
	s_xor_b64 s[14:15], exec, s[14:15]
	ds_write_b16 v9, v0 offset:86
	v_xor_b32_e32 v0, 0xffff8000, v0
	s_or_saveexec_b64 s[14:15], s[14:15]
	v_mov_b32_e32 v4, 0xa0
	s_xor_b64 exec, exec, s[14:15]
	v_mov_b32_e32 v4, 64
	ds_write_b16 v9, v0 offset:22
	s_or_b64 exec, exec, s[14:15]
	v_sub_u32_e32 v1, v4, v1
	v_lshl_add_u32 v1, v1, 1, v8
	ds_write_b16 v1, v0
	v_or_b32_e32 v0, 12, v10
	v_cmp_lt_u32_e32 vcc, 32, v0
	s_and_saveexec_b64 s[14:15], vcc
	s_xor_b64 s[14:15], exec, s[14:15]
	v_xor_b32_e32 v1, 0xffff8000, v2
	ds_write_b16 v9, v2 offset:88
	s_or_saveexec_b64 s[14:15], s[14:15]
	v_mov_b32_e32 v4, 0xa0
	s_xor_b64 exec, exec, s[14:15]
	v_mov_b32_e32 v4, 64
	v_mov_b32_e32 v1, v2
	ds_write_b16 v9, v2 offset:24
	s_or_b64 exec, exec, s[14:15]
	v_sub_u32_e32 v0, v4, v0
	v_lshl_add_u32 v0, v0, 1, v8
	ds_write_b16 v0, v1
	v_or_b32_e32 v1, 13, v10
	v_lshrrev_b32_e32 v0, 16, v2
	v_cmp_lt_u32_e32 vcc, 32, v1
	s_and_saveexec_b64 s[14:15], vcc
	s_xor_b64 s[14:15], exec, s[14:15]
	ds_write_b16 v9, v0 offset:90
	v_xor_b32_e32 v0, 0xffff8000, v0
	s_or_saveexec_b64 s[14:15], s[14:15]
	v_mov_b32_e32 v2, 0xa0
	s_xor_b64 exec, exec, s[14:15]
	v_mov_b32_e32 v2, 64
	ds_write_b16 v9, v0 offset:26
	s_or_b64 exec, exec, s[14:15]
	v_sub_u32_e32 v1, v2, v1
	v_lshl_add_u32 v1, v1, 1, v8
	ds_write_b16 v1, v0
	v_or_b32_e32 v0, 14, v10
	v_cmp_lt_u32_e32 vcc, 32, v0
	s_and_saveexec_b64 s[14:15], vcc
	s_xor_b64 s[14:15], exec, s[14:15]
	v_xor_b32_e32 v1, 0xffff8000, v3
	ds_write_b16 v9, v3 offset:92
	s_or_saveexec_b64 s[14:15], s[14:15]
	v_mov_b32_e32 v2, 0xa0
	s_xor_b64 exec, exec, s[14:15]
	v_mov_b32_e32 v2, 64
	v_mov_b32_e32 v1, v3
	ds_write_b16 v9, v3 offset:28
	s_or_b64 exec, exec, s[14:15]
	v_sub_u32_e32 v0, v2, v0
	v_lshl_add_u32 v0, v0, 1, v8
	ds_write_b16 v0, v1
	v_or_b32_e32 v1, 15, v10
	v_lshrrev_b32_e32 v0, 16, v3
	v_cmp_lt_u32_e32 vcc, 32, v1
	s_and_saveexec_b64 s[14:15], vcc
	s_xor_b64 s[14:15], exec, s[14:15]
	ds_write_b16 v9, v0 offset:94
	v_xor_b32_e32 v0, 0xffff8000, v0
	s_or_saveexec_b64 s[14:15], s[14:15]
	v_mov_b32_e32 v2, 0xa0
	s_xor_b64 exec, exec, s[14:15]
	v_mov_b32_e32 v2, 64
	ds_write_b16 v9, v0 offset:30
	s_or_b64 exec, exec, s[14:15]
	v_sub_u32_e32 v1, v2, v1
	v_lshl_add_u32 v1, v1, 1, v8
	ds_write_b16 v1, v0
	v_lshlrev_b32_e32 v0, 5, v194
	v_and_b32_e32 v45, 0x60, v0
	v_or_b32_e32 v0, v45, v195
	v_readlane_b32 s14, v255, 36
	v_lshlrev_b32_e32 v168, 8, v0
	v_readlane_b32 s15, v255, 37
	v_lshlrev_b32_e32 v2, 4, v193
	v_mov_b32_e32 v3, v169
	v_lshl_add_u64 v[0:1], s[14:15], 0, v[168:169]
	v_lshl_add_u64 v[32:33], v[0:1], 0, v[2:3]
	v_lshl_add_u64 v[0:1], s[48:49], 0, v[168:169]
	s_waitcnt lgkmcnt(0)
	s_barrier
	v_lshl_add_u64 v[34:35], v[0:1], 0, v[2:3]
	global_load_dwordx4 v[100:103], v[32:33], off
	global_load_dwordx4 v[104:107], v[34:35], off
	global_load_dwordx4 v[108:111], v[32:33], off offset:32
	global_load_dwordx4 v[112:115], v[34:35], off offset:32
	global_load_dwordx4 v[116:119], v[32:33], off offset:64
	global_load_dwordx4 v[120:123], v[34:35], off offset:64
	global_load_dwordx4 v[124:127], v[32:33], off offset:96
	global_load_dwordx4 v[128:131], v[34:35], off offset:96
	global_load_dwordx4 v[132:135], v[32:33], off offset:128
	global_load_dwordx4 v[136:139], v[34:35], off offset:128
	global_load_dwordx4 v[140:143], v[32:33], off offset:160
	global_load_dwordx4 v[144:147], v[34:35], off offset:160
	global_load_dwordx4 v[148:151], v[32:33], off offset:192
	global_load_dwordx4 v[152:155], v[34:35], off offset:192
	global_load_dwordx4 v[156:159], v[32:33], off offset:224
	global_load_dwordx4 v[160:163], v[34:35], off offset:224
	v_ashrrev_i32_e32 v0, 3, v97
	v_lshlrev_b32_e32 v2, 2, v98
	v_and_b32_e32 v44, 0xffffffe0, v0
	v_and_b32_e32 v1, 16, v97
	v_and_b32_e32 v2, 12, v2
	v_bfe_u32 v0, v97, 2, 2
	v_or3_b32 v3, v2, v1, v44
	v_lshlrev_b32_e32 v3, 1, v3
	v_lshl_or_b32 v0, v193, 3, v0
	v_or3_b32 v1, v44, v1, v2
	v_mul_u32_u24_e32 v2, 0x140, v0
	v_mad_u32_u24 v38, v0, s60, v3
	v_lshl_add_u32 v46, v1, 1, v2
	ds_read_b64_tr_b16 v[48:49], v38
	ds_read_b64_tr_b16 v[50:51], v38 offset:1280
	ds_read_b64_tr_b16 v[20:21], v46 offset:128
	ds_read_b64_tr_b16 v[22:23], v46 offset:1408
	s_mov_b32 s5, 0x8000
	s_mov_b32 s14, 0x5040100
	s_waitcnt lgkmcnt(2)
	v_xor_b32_e32 v36, 0x8000, v51
	v_xor_b32_sdwa v37, s5, v51 dst_sel:DWORD dst_unused:UNUSED_PAD src0_sel:DWORD src1_sel:WORD_1
	v_readlane_b32 s16, v254, 62
	v_readlane_b32 s17, v254, 63
	s_waitcnt vmcnt(15)
	v_mfma_f32_32x32x16_bf16 v[0:15], v[100:103], v[48:51], 0
	v_perm_b32 v51, v37, v36, s14
	v_xor_b32_e32 v36, 0x8000, v50
	v_xor_b32_sdwa v37, s5, v50 dst_sel:DWORD dst_unused:UNUSED_PAD src0_sel:DWORD src1_sel:WORD_1
	v_perm_b32 v50, v37, v36, s14
	v_xor_b32_e32 v36, 0x8000, v49
	v_xor_b32_sdwa v37, s5, v49 dst_sel:DWORD dst_unused:UNUSED_PAD src0_sel:DWORD src1_sel:WORD_1
	v_perm_b32 v49, v37, v36, s14
	s_waitcnt vmcnt(14) lgkmcnt(0)
	v_mfma_f32_32x32x16_bf16 v[0:15], v[104:107], v[20:23], v[0:15]
	v_xor_b32_e32 v36, 0x8000, v48
	v_xor_b32_sdwa v37, s5, v48 dst_sel:DWORD dst_unused:UNUSED_PAD src0_sel:DWORD src1_sel:WORD_1
	v_perm_b32 v48, v37, v36, s14
	v_mfma_f32_32x32x16_bf16 v[16:31], v[100:103], v[20:23], 0
	s_nop 0
	v_mfma_f32_32x32x16_bf16 v[16:31], v[104:107], v[48:51], v[16:31]
	ds_read_b64_tr_b16 v[52:53], v38 offset:5120
	ds_read_b64_tr_b16 v[54:55], v38 offset:6400
	ds_read_b64_tr_b16 v[56:57], v46 offset:5248
	ds_read_b64_tr_b16 v[58:59], v46 offset:6528
	s_waitcnt lgkmcnt(2)
	v_xor_b32_e32 v36, 0x8000, v55
	v_xor_b32_sdwa v37, s5, v55 dst_sel:DWORD dst_unused:UNUSED_PAD src0_sel:DWORD src1_sel:WORD_1
	s_waitcnt vmcnt(13)
	v_mfma_f32_32x32x16_bf16 v[0:15], v[108:111], v[52:55], v[0:15]
	s_waitcnt lgkmcnt(0)
	v_mfma_f32_32x32x16_bf16 v[16:31], v[108:111], v[56:59], v[16:31]
	v_perm_b32 v43, v37, v36, s14
	v_xor_b32_e32 v36, 0x8000, v54
	v_xor_b32_sdwa v37, s5, v54 dst_sel:DWORD dst_unused:UNUSED_PAD src0_sel:DWORD src1_sel:WORD_1
	v_perm_b32 v42, v37, v36, s14
	v_xor_b32_e32 v36, 0x8000, v53
	v_xor_b32_sdwa v37, s5, v53 dst_sel:DWORD dst_unused:UNUSED_PAD src0_sel:DWORD src1_sel:WORD_1
	v_perm_b32 v41, v37, v36, s14
	v_xor_b32_e32 v36, 0x8000, v52
	v_xor_b32_sdwa v37, s5, v52 dst_sel:DWORD dst_unused:UNUSED_PAD src0_sel:DWORD src1_sel:WORD_1
	v_perm_b32 v40, v37, v36, s14
	s_waitcnt vmcnt(12)
	v_mfma_f32_32x32x16_bf16 v[0:15], v[112:115], v[56:59], v[0:15]
	v_mfma_f32_32x32x16_bf16 v[16:31], v[112:115], v[40:43], v[16:31]
	ds_read_b64_tr_b16 v[52:53], v38 offset:10240
	ds_read_b64_tr_b16 v[54:55], v38 offset:11520
	ds_read_b64_tr_b16 v[56:57], v46 offset:10368
	ds_read_b64_tr_b16 v[58:59], v46 offset:11648
	s_waitcnt lgkmcnt(2)
	v_xor_b32_e32 v36, 0x8000, v55
	v_xor_b32_sdwa v37, s5, v55 dst_sel:DWORD dst_unused:UNUSED_PAD src0_sel:DWORD src1_sel:WORD_1
	s_waitcnt vmcnt(11)
	v_mfma_f32_32x32x16_bf16 v[0:15], v[116:119], v[52:55], v[0:15]
	s_waitcnt lgkmcnt(0)
	v_mfma_f32_32x32x16_bf16 v[16:31], v[116:119], v[56:59], v[16:31]
	v_perm_b32 v43, v37, v36, s14
	v_xor_b32_e32 v36, 0x8000, v54
	v_xor_b32_sdwa v37, s5, v54 dst_sel:DWORD dst_unused:UNUSED_PAD src0_sel:DWORD src1_sel:WORD_1
	v_perm_b32 v42, v37, v36, s14
	v_xor_b32_e32 v36, 0x8000, v53
	v_xor_b32_sdwa v37, s5, v53 dst_sel:DWORD dst_unused:UNUSED_PAD src0_sel:DWORD src1_sel:WORD_1
	v_perm_b32 v41, v37, v36, s14
	v_xor_b32_e32 v36, 0x8000, v52
	v_xor_b32_sdwa v37, s5, v52 dst_sel:DWORD dst_unused:UNUSED_PAD src0_sel:DWORD src1_sel:WORD_1
	v_perm_b32 v40, v37, v36, s14
	s_waitcnt vmcnt(10)
	v_mfma_f32_32x32x16_bf16 v[0:15], v[120:123], v[56:59], v[0:15]
	v_mfma_f32_32x32x16_bf16 v[16:31], v[120:123], v[40:43], v[16:31]
	ds_read_b64_tr_b16 v[52:53], v38 offset:15360
	ds_read_b64_tr_b16 v[54:55], v38 offset:16640
	ds_read_b64_tr_b16 v[56:57], v46 offset:15488
	ds_read_b64_tr_b16 v[58:59], v46 offset:16768
	s_waitcnt lgkmcnt(2)
	v_xor_b32_e32 v36, 0x8000, v55
	v_xor_b32_sdwa v37, s5, v55 dst_sel:DWORD dst_unused:UNUSED_PAD src0_sel:DWORD src1_sel:WORD_1
	s_waitcnt vmcnt(9)
	v_mfma_f32_32x32x16_bf16 v[0:15], v[124:127], v[52:55], v[0:15]
	s_waitcnt lgkmcnt(0)
	v_mfma_f32_32x32x16_bf16 v[16:31], v[124:127], v[56:59], v[16:31]
	v_perm_b32 v43, v37, v36, s14
	v_xor_b32_e32 v36, 0x8000, v54
	v_xor_b32_sdwa v37, s5, v54 dst_sel:DWORD dst_unused:UNUSED_PAD src0_sel:DWORD src1_sel:WORD_1
	v_perm_b32 v42, v37, v36, s14
	v_xor_b32_e32 v36, 0x8000, v53
	v_xor_b32_sdwa v37, s5, v53 dst_sel:DWORD dst_unused:UNUSED_PAD src0_sel:DWORD src1_sel:WORD_1
	v_perm_b32 v41, v37, v36, s14
	v_xor_b32_e32 v36, 0x8000, v52
	v_xor_b32_sdwa v37, s5, v52 dst_sel:DWORD dst_unused:UNUSED_PAD src0_sel:DWORD src1_sel:WORD_1
	v_perm_b32 v40, v37, v36, s14
	s_waitcnt vmcnt(8)
	v_mfma_f32_32x32x16_bf16 v[0:15], v[128:131], v[56:59], v[0:15]
	v_mfma_f32_32x32x16_bf16 v[16:31], v[128:131], v[40:43], v[16:31]
	ds_read_b64_tr_b16 v[52:53], v38 offset:20480
	ds_read_b64_tr_b16 v[54:55], v38 offset:21760
	ds_read_b64_tr_b16 v[56:57], v46 offset:20608
	ds_read_b64_tr_b16 v[58:59], v46 offset:21888
	s_waitcnt lgkmcnt(2)
	v_xor_b32_e32 v36, 0x8000, v55
	v_xor_b32_sdwa v37, s5, v55 dst_sel:DWORD dst_unused:UNUSED_PAD src0_sel:DWORD src1_sel:WORD_1
	s_waitcnt vmcnt(7)
	v_mfma_f32_32x32x16_bf16 v[0:15], v[132:135], v[52:55], v[0:15]
	s_waitcnt lgkmcnt(0)
	v_mfma_f32_32x32x16_bf16 v[16:31], v[132:135], v[56:59], v[16:31]
	v_perm_b32 v43, v37, v36, s14
	v_xor_b32_e32 v36, 0x8000, v54
	v_xor_b32_sdwa v37, s5, v54 dst_sel:DWORD dst_unused:UNUSED_PAD src0_sel:DWORD src1_sel:WORD_1
	v_perm_b32 v42, v37, v36, s14
	v_xor_b32_e32 v36, 0x8000, v53
	v_xor_b32_sdwa v37, s5, v53 dst_sel:DWORD dst_unused:UNUSED_PAD src0_sel:DWORD src1_sel:WORD_1
	v_perm_b32 v41, v37, v36, s14
	v_xor_b32_e32 v36, 0x8000, v52
	v_xor_b32_sdwa v37, s5, v52 dst_sel:DWORD dst_unused:UNUSED_PAD src0_sel:DWORD src1_sel:WORD_1
	v_perm_b32 v40, v37, v36, s14
	s_waitcnt vmcnt(6)
	v_mfma_f32_32x32x16_bf16 v[0:15], v[136:139], v[56:59], v[0:15]
	v_mfma_f32_32x32x16_bf16 v[16:31], v[136:139], v[40:43], v[16:31]
	ds_read_b64_tr_b16 v[52:53], v38 offset:25600
	ds_read_b64_tr_b16 v[54:55], v38 offset:26880
	ds_read_b64_tr_b16 v[56:57], v46 offset:25728
	ds_read_b64_tr_b16 v[58:59], v46 offset:27008
	s_waitcnt lgkmcnt(2)
	v_xor_b32_e32 v36, 0x8000, v55
	v_xor_b32_sdwa v37, s5, v55 dst_sel:DWORD dst_unused:UNUSED_PAD src0_sel:DWORD src1_sel:WORD_1
	s_waitcnt vmcnt(5)
	v_mfma_f32_32x32x16_bf16 v[0:15], v[140:143], v[52:55], v[0:15]
	s_waitcnt lgkmcnt(0)
	v_mfma_f32_32x32x16_bf16 v[16:31], v[140:143], v[56:59], v[16:31]
	v_perm_b32 v43, v37, v36, s14
	v_xor_b32_e32 v36, 0x8000, v54
	v_xor_b32_sdwa v37, s5, v54 dst_sel:DWORD dst_unused:UNUSED_PAD src0_sel:DWORD src1_sel:WORD_1
	v_perm_b32 v42, v37, v36, s14
	v_xor_b32_e32 v36, 0x8000, v53
	v_xor_b32_sdwa v37, s5, v53 dst_sel:DWORD dst_unused:UNUSED_PAD src0_sel:DWORD src1_sel:WORD_1
	v_perm_b32 v41, v37, v36, s14
	v_xor_b32_e32 v36, 0x8000, v52
	v_xor_b32_sdwa v37, s5, v52 dst_sel:DWORD dst_unused:UNUSED_PAD src0_sel:DWORD src1_sel:WORD_1
	v_perm_b32 v40, v37, v36, s14
	s_waitcnt vmcnt(4)
	v_mfma_f32_32x32x16_bf16 v[0:15], v[144:147], v[56:59], v[0:15]
	v_mfma_f32_32x32x16_bf16 v[16:31], v[144:147], v[40:43], v[16:31]
	ds_read_b64_tr_b16 v[52:53], v38 offset:30720
	ds_read_b64_tr_b16 v[54:55], v38 offset:32000
	ds_read_b64_tr_b16 v[56:57], v46 offset:30848
	ds_read_b64_tr_b16 v[58:59], v46 offset:32128
	s_waitcnt lgkmcnt(2)
	v_xor_b32_e32 v36, 0x8000, v55
	v_xor_b32_sdwa v37, s5, v55 dst_sel:DWORD dst_unused:UNUSED_PAD src0_sel:DWORD src1_sel:WORD_1
	s_waitcnt vmcnt(3) lgkmcnt(0)
	v_mfma_f32_32x32x16_bf16 v[16:31], v[148:151], v[56:59], v[16:31]
	v_mfma_f32_32x32x16_bf16 v[0:15], v[148:151], v[52:55], v[0:15]
	v_perm_b32 v43, v37, v36, s14
	v_xor_b32_e32 v36, 0x8000, v54
	v_xor_b32_sdwa v37, s5, v54 dst_sel:DWORD dst_unused:UNUSED_PAD src0_sel:DWORD src1_sel:WORD_1
	v_perm_b32 v42, v37, v36, s14
	v_xor_b32_e32 v36, 0x8000, v53
	v_xor_b32_sdwa v37, s5, v53 dst_sel:DWORD dst_unused:UNUSED_PAD src0_sel:DWORD src1_sel:WORD_1
	v_perm_b32 v41, v37, v36, s14
	v_xor_b32_e32 v36, 0x8000, v52
	v_xor_b32_sdwa v37, s5, v52 dst_sel:DWORD dst_unused:UNUSED_PAD src0_sel:DWORD src1_sel:WORD_1
	v_perm_b32 v40, v37, v36, s14
	s_waitcnt vmcnt(2)
	v_mfma_f32_32x32x16_bf16 v[0:15], v[152:155], v[56:59], v[0:15]
	v_mfma_f32_32x32x16_bf16 v[16:31], v[152:155], v[40:43], v[16:31]
	s_nop 0
	ds_read_b64_tr_b16 v[36:37], v38 offset:35840
	ds_read_b64_tr_b16 v[38:39], v38 offset:37120
	ds_read_b64_tr_b16 v[48:49], v46 offset:35968
	ds_read_b64_tr_b16 v[50:51], v46 offset:37248
	s_waitcnt vmcnt(1) lgkmcnt(0)
	v_mfma_f32_32x32x16_bf16 v[16:31], v[156:159], v[48:51], v[16:31]
	v_mfma_f32_32x32x16_bf16 v[0:15], v[156:159], v[36:39], v[0:15]
	v_xor_b32_e32 v40, 0x8000, v39
	v_xor_b32_sdwa v39, s5, v39 dst_sel:DWORD dst_unused:UNUSED_PAD src0_sel:DWORD src1_sel:WORD_1
	v_perm_b32 v39, v39, v40, s14
	v_xor_b32_e32 v40, 0x8000, v38
	v_xor_b32_sdwa v38, s5, v38 dst_sel:DWORD dst_unused:UNUSED_PAD src0_sel:DWORD src1_sel:WORD_1
	v_perm_b32 v38, v38, v40, s14
	v_xor_b32_e32 v40, 0x8000, v37
	v_xor_b32_sdwa v37, s5, v37 dst_sel:DWORD dst_unused:UNUSED_PAD src0_sel:DWORD src1_sel:WORD_1
	v_perm_b32 v37, v37, v40, s14
	v_xor_b32_e32 v40, 0x8000, v36
	v_xor_b32_sdwa v36, s5, v36 dst_sel:DWORD dst_unused:UNUSED_PAD src0_sel:DWORD src1_sel:WORD_1
	v_perm_b32 v36, v36, v40, s14
	s_and_b64 s[14:15], s[42:43], exec
	s_movk_i32 s5, 0xfff
	s_waitcnt vmcnt(0)
	v_mfma_f32_32x32x16_bf16 v[16:31], v[160:163], v[36:39], v[16:31]
	v_lshl_or_b32 v36, v193, 2, v45
	s_cselect_b32 s5, s5, 0x1fff
	v_cndmask_b32_e64 v37, 0, 1, s[42:43]
	s_lshl_b32 s14, s56, 8
	s_add_u32 s42, s16, s14
	s_addc_u32 s43, s17, 0
	s_mul_i32 s14, s55, 5
	v_mfma_f32_32x32x16_bf16 v[0:15], v[160:163], v[48:51], v[0:15]
	v_mul_u32_u24_e32 v32, s55, v36
	v_and_b32_e32 v32, s5, v32
	v_lshlrev_b32_e32 v32, v37, v32
	v_lshlrev_b32_e32 v32, 2, v32
	v_add_u32_e32 v240, 0, v36
	v_mul_u32_u24_e32 v240, s55, v240
	v_and_b32_e32 v240, s5, v240
	v_lshlrev_b32_e32 v240, v37, v240
	v_lshlrev_b32_e32 v240, 2, v240
	global_load_dword v208, v240, s[44:45]
	global_load_dword v224, v240, s[94:95]
	v_add_u32_e32 v240, 1, v36
	v_mul_u32_u24_e32 v240, s55, v240
	v_and_b32_e32 v240, s5, v240
	v_lshlrev_b32_e32 v240, v37, v240
	v_lshlrev_b32_e32 v240, 2, v240
	global_load_dword v209, v240, s[44:45]
	global_load_dword v225, v240, s[94:95]
	v_add_u32_e32 v240, 2, v36
	v_mul_u32_u24_e32 v240, s55, v240
	v_and_b32_e32 v240, s5, v240
	v_lshlrev_b32_e32 v240, v37, v240
	v_lshlrev_b32_e32 v240, 2, v240
	global_load_dword v210, v240, s[44:45]
	global_load_dword v226, v240, s[94:95]
	v_add_u32_e32 v240, 3, v36
	v_mul_u32_u24_e32 v240, s55, v240
	v_and_b32_e32 v240, s5, v240
	v_lshlrev_b32_e32 v240, v37, v240
	v_lshlrev_b32_e32 v240, 2, v240
	global_load_dword v211, v240, s[44:45]
	global_load_dword v227, v240, s[94:95]
	v_add_u32_e32 v240, 8, v36
	v_mul_u32_u24_e32 v240, s55, v240
	v_and_b32_e32 v240, s5, v240
	v_lshlrev_b32_e32 v240, v37, v240
	v_lshlrev_b32_e32 v240, 2, v240
	global_load_dword v212, v240, s[44:45]
	global_load_dword v228, v240, s[94:95]
	v_add_u32_e32 v240, 9, v36
	v_mul_u32_u24_e32 v240, s55, v240
	v_and_b32_e32 v240, s5, v240
	v_lshlrev_b32_e32 v240, v37, v240
	v_lshlrev_b32_e32 v240, 2, v240
	global_load_dword v213, v240, s[44:45]
	global_load_dword v229, v240, s[94:95]
	v_add_u32_e32 v240, 10, v36
	v_mul_u32_u24_e32 v240, s55, v240
	v_and_b32_e32 v240, s5, v240
	v_lshlrev_b32_e32 v240, v37, v240
	v_lshlrev_b32_e32 v240, 2, v240
	global_load_dword v214, v240, s[44:45]
	global_load_dword v230, v240, s[94:95]
	v_add_u32_e32 v240, 11, v36
	v_mul_u32_u24_e32 v240, s55, v240
	v_and_b32_e32 v240, s5, v240
	v_lshlrev_b32_e32 v240, v37, v240
	v_lshlrev_b32_e32 v240, 2, v240
	global_load_dword v215, v240, s[44:45]
	global_load_dword v231, v240, s[94:95]
	v_add_u32_e32 v240, 16, v36
	v_mul_u32_u24_e32 v240, s55, v240
	v_and_b32_e32 v240, s5, v240
	v_lshlrev_b32_e32 v240, v37, v240
	v_lshlrev_b32_e32 v240, 2, v240
	global_load_dword v216, v240, s[44:45]
	global_load_dword v232, v240, s[94:95]
	v_add_u32_e32 v240, 17, v36
	v_mul_u32_u24_e32 v240, s55, v240
	v_and_b32_e32 v240, s5, v240
	v_lshlrev_b32_e32 v240, v37, v240
	v_lshlrev_b32_e32 v240, 2, v240
	global_load_dword v217, v240, s[44:45]
	global_load_dword v233, v240, s[94:95]
	v_add_u32_e32 v240, 18, v36
	v_mul_u32_u24_e32 v240, s55, v240
	v_and_b32_e32 v240, s5, v240
	v_lshlrev_b32_e32 v240, v37, v240
	v_lshlrev_b32_e32 v240, 2, v240
	global_load_dword v218, v240, s[44:45]
	global_load_dword v234, v240, s[94:95]
	v_add_u32_e32 v240, 19, v36
	v_mul_u32_u24_e32 v240, s55, v240
	v_and_b32_e32 v240, s5, v240
	v_lshlrev_b32_e32 v240, v37, v240
	v_lshlrev_b32_e32 v240, 2, v240
	global_load_dword v219, v240, s[44:45]
	global_load_dword v235, v240, s[94:95]
	v_add_u32_e32 v240, 24, v36
	v_mul_u32_u24_e32 v240, s55, v240
	v_and_b32_e32 v240, s5, v240
	v_lshlrev_b32_e32 v240, v37, v240
	v_lshlrev_b32_e32 v240, 2, v240
	global_load_dword v220, v240, s[44:45]
	global_load_dword v236, v240, s[94:95]
	v_add_u32_e32 v240, 25, v36
	v_mul_u32_u24_e32 v240, s55, v240
	v_and_b32_e32 v240, s5, v240
	v_lshlrev_b32_e32 v240, v37, v240
	v_lshlrev_b32_e32 v240, 2, v240
	global_load_dword v221, v240, s[44:45]
	global_load_dword v237, v240, s[94:95]
	v_add_u32_e32 v240, 26, v36
	v_mul_u32_u24_e32 v240, s55, v240
	v_and_b32_e32 v240, s5, v240
	v_lshlrev_b32_e32 v240, v37, v240
	v_lshlrev_b32_e32 v240, 2, v240
	global_load_dword v222, v240, s[44:45]
	global_load_dword v238, v240, s[94:95]
	v_add_u32_e32 v240, 27, v36
	v_mul_u32_u24_e32 v240, s55, v240
	v_and_b32_e32 v240, s5, v240
	v_lshlrev_b32_e32 v240, v37, v240
	v_lshlrev_b32_e32 v240, 2, v240
	global_load_dword v223, v240, s[44:45]
	global_load_dword v239, v240, s[94:95]
	v_lshlrev_b32_e32 v32, s26, v36
	v_add_u32_e32 v32, s27, v32
	v_ashrrev_i32_e32 v33, 31, v32
	v_lshlrev_b64 v[32:33], 10, v[32:33]
	v_or_b32_e32 v34, v44, v195
	v_lshl_add_u64 v[38:39], s[42:43], 0, v[32:33]
	v_ashrrev_i32_e32 v35, 31, v34
	s_waitcnt vmcnt(0)
	v_mul_f32_e32 v32, v16, v224
	v_fmac_f32_e32 v32, v0, v208
	v_mul_f32_e32 v0, v0, v224
	v_fma_f32 v0, v16, v208, -v0
	v_cvt_pk_bf16_f32 v16, v32, s0
	v_lshlrev_b64 v[32:33], 1, v[34:35]
	v_ashrrev_i32_e32 v35, 31, v44
	v_lshl_add_u64 v[40:41], v[38:39], 0, v[32:33]
	v_lshlrev_b64 v[34:35], 1, v[34:35]
	global_store_short v[40:41], v16, off
	v_cvt_pk_bf16_f32 v0, v0, s0
	v_lshl_add_u64 v[38:39], v[38:39], 0, v[34:35]
	v_mad_u32_u24 v16, v36, s55, s55
	global_store_short v[38:39], v0, off offset:128
	v_and_b32_e32 v38, s5, v16
	v_lshlrev_b32_e32 v38, v37, v38
	v_lshlrev_b32_e32 v38, 2, v38
	v_or_b32_e32 v0, 1, v36
	v_lshlrev_b32_e32 v0, s26, v0
	v_add_u32_e32 v38, s27, v0
	v_ashrrev_i32_e32 v39, 31, v38
	v_lshlrev_b64 v[38:39], 10, v[38:39]
	v_lshl_add_u64 v[38:39], s[42:43], 0, v[38:39]
	v_mul_f32_e32 v0, v17, v225
	v_fmac_f32_e32 v0, v1, v209
	v_mul_f32_e32 v1, v1, v225
	v_fma_f32 v17, v17, v209, -v1
	v_cvt_pk_bf16_f32 v40, v0, s0
	v_lshl_add_u64 v[0:1], v[38:39], 0, v[32:33]
	global_store_short v[0:1], v40, off
	v_cvt_pk_bf16_f32 v17, v17, s0
	v_lshl_add_u64 v[0:1], v[38:39], 0, v[34:35]
	v_add_u32_e32 v38, s55, v16
	global_store_short v[0:1], v17, off offset:128
	v_and_b32_e32 v1, s5, v38
	v_lshlrev_b32_e32 v1, v37, v1
	v_lshlrev_b32_e32 v1, 2, v1
	v_or_b32_e32 v0, 2, v36
	v_lshlrev_b32_e32 v0, s26, v0
	v_add_u32_e32 v0, s27, v0
	v_ashrrev_i32_e32 v1, 31, v0
	v_lshlrev_b64 v[0:1], 10, v[0:1]
	v_lshl_add_u64 v[0:1], s[42:43], 0, v[0:1]
	v_mul_f32_e32 v39, v18, v226
	v_fmac_f32_e32 v39, v2, v210
	v_mul_f32_e32 v2, v2, v226
	v_fma_f32 v2, v18, v210, -v2
	v_cvt_pk_bf16_f32 v18, v39, s0
	v_lshl_add_u64 v[16:17], v[0:1], 0, v[32:33]
	global_store_short v[16:17], v18, off
	v_cvt_pk_bf16_f32 v2, v2, s0
	v_lshl_add_u64 v[0:1], v[0:1], 0, v[34:35]
	v_add_u32_e32 v16, s55, v38
	global_store_short v[0:1], v2, off offset:128
	v_and_b32_e32 v1, s5, v16
	v_lshlrev_b32_e32 v1, v37, v1
	v_lshlrev_b32_e32 v1, 2, v1
	v_or_b32_e32 v0, 3, v36
	v_lshlrev_b32_e32 v0, s26, v0
	v_add_u32_e32 v0, s27, v0
	v_ashrrev_i32_e32 v1, 31, v0
	v_lshlrev_b64 v[0:1], 10, v[0:1]
	v_lshl_add_u64 v[0:1], s[42:43], 0, v[0:1]
	v_add_u32_e32 v16, s14, v16
	v_mul_f32_e32 v18, v19, v227
	v_fmac_f32_e32 v18, v3, v211
	v_mul_f32_e32 v3, v3, v227
	v_fma_f32 v17, v19, v211, -v3
	v_cvt_pk_bf16_f32 v18, v18, s0
	v_lshl_add_u64 v[2:3], v[0:1], 0, v[32:33]
	global_store_short v[2:3], v18, off
	v_cvt_pk_bf16_f32 v2, v17, s0
	v_lshl_add_u64 v[0:1], v[0:1], 0, v[34:35]
	global_store_short v[0:1], v2, off offset:128
	v_and_b32_e32 v1, s5, v16
	v_lshlrev_b32_e32 v1, v37, v1
	v_lshlrev_b32_e32 v1, 2, v1
	v_or_b32_e32 v0, 8, v36
	v_lshlrev_b32_e32 v0, s26, v0
	v_add_u32_e32 v0, s27, v0
	v_ashrrev_i32_e32 v1, 31, v0
	v_lshlrev_b64 v[0:1], 10, v[0:1]
	v_lshl_add_u64 v[0:1], s[42:43], 0, v[0:1]
	v_mul_f32_e32 v17, v20, v228
	v_fmac_f32_e32 v17, v4, v212
	v_mul_f32_e32 v3, v4, v228
	v_fma_f32 v4, v20, v212, -v3
	v_cvt_pk_bf16_f32 v17, v17, s0
	v_lshl_add_u64 v[2:3], v[0:1], 0, v[32:33]
	global_store_short v[2:3], v17, off
	v_cvt_pk_bf16_f32 v2, v4, s0
	v_lshl_add_u64 v[0:1], v[0:1], 0, v[34:35]
	v_add_u32_e32 v4, s55, v16
	global_store_short v[0:1], v2, off offset:128
	v_and_b32_e32 v1, s5, v4
	v_lshlrev_b32_e32 v1, v37, v1
	v_lshlrev_b32_e32 v1, 2, v1
	v_or_b32_e32 v0, 9, v36
	v_lshlrev_b32_e32 v0, s26, v0
	v_add_u32_e32 v0, s27, v0
	v_ashrrev_i32_e32 v1, 31, v0
	v_lshlrev_b64 v[0:1], 10, v[0:1]
	v_lshl_add_u64 v[0:1], s[42:43], 0, v[0:1]
	v_add_u32_e32 v4, s55, v4
	v_mul_f32_e32 v16, v21, v229
	v_fmac_f32_e32 v16, v5, v213
	v_mul_f32_e32 v3, v5, v229
	v_fma_f32 v5, v21, v213, -v3
	v_cvt_pk_bf16_f32 v16, v16, s0
	v_lshl_add_u64 v[2:3], v[0:1], 0, v[32:33]
	global_store_short v[2:3], v16, off
	v_cvt_pk_bf16_f32 v2, v5, s0
	v_lshl_add_u64 v[0:1], v[0:1], 0, v[34:35]
	global_store_short v[0:1], v2, off offset:128
	v_and_b32_e32 v1, s5, v4
	v_lshlrev_b32_e32 v1, v37, v1
	v_lshlrev_b32_e32 v1, 2, v1
	v_or_b32_e32 v0, 10, v36
	v_lshlrev_b32_e32 v0, s26, v0
	v_add_u32_e32 v0, s27, v0
	v_ashrrev_i32_e32 v1, 31, v0
	v_lshlrev_b64 v[0:1], 10, v[0:1]
	v_lshl_add_u64 v[0:1], s[42:43], 0, v[0:1]
	v_add_u32_e32 v4, s55, v4
	v_mul_f32_e32 v5, v22, v230
	v_fmac_f32_e32 v5, v6, v214
	v_mul_f32_e32 v3, v6, v230
	v_fma_f32 v6, v22, v214, -v3
	v_cvt_pk_bf16_f32 v5, v5, s0
	v_lshl_add_u64 v[2:3], v[0:1], 0, v[32:33]
	global_store_short v[2:3], v5, off
	v_cvt_pk_bf16_f32 v2, v6, s0
	v_lshl_add_u64 v[0:1], v[0:1], 0, v[34:35]
	global_store_short v[0:1], v2, off offset:128
	v_and_b32_e32 v1, s5, v4
	v_lshlrev_b32_e32 v1, v37, v1
	v_lshlrev_b32_e32 v1, 2, v1
	v_or_b32_e32 v0, 11, v36
	v_lshlrev_b32_e32 v0, s26, v0
	v_add_u32_e32 v0, s27, v0
	v_ashrrev_i32_e32 v1, 31, v0
	v_lshlrev_b64 v[0:1], 10, v[0:1]
	v_lshl_add_u64 v[0:1], s[42:43], 0, v[0:1]
	v_add_u32_e32 v4, s14, v4
	v_mul_f32_e32 v5, v23, v231
	v_fmac_f32_e32 v5, v7, v215
	v_mul_f32_e32 v3, v7, v231
	v_fma_f32 v6, v23, v215, -v3
	v_cvt_pk_bf16_f32 v5, v5, s0
	v_lshl_add_u64 v[2:3], v[0:1], 0, v[32:33]
	global_store_short v[2:3], v5, off
	v_cvt_pk_bf16_f32 v2, v6, s0
	v_lshl_add_u64 v[0:1], v[0:1], 0, v[34:35]
	global_store_short v[0:1], v2, off offset:128
	v_and_b32_e32 v1, s5, v4
	v_lshlrev_b32_e32 v1, v37, v1
	v_lshlrev_b32_e32 v1, 2, v1
	v_or_b32_e32 v0, 16, v36
	v_lshlrev_b32_e32 v0, s26, v0
	v_add_u32_e32 v0, s27, v0
	v_ashrrev_i32_e32 v1, 31, v0
	v_lshlrev_b64 v[0:1], 10, v[0:1]
	v_lshl_add_u64 v[0:1], s[42:43], 0, v[0:1]
	v_add_u32_e32 v4, s55, v4
	v_mul_f32_e32 v5, v24, v232
	v_fmac_f32_e32 v5, v8, v216
	v_mul_f32_e32 v3, v8, v232
	v_fma_f32 v6, v24, v216, -v3
	v_cvt_pk_bf16_f32 v5, v5, s0
	v_lshl_add_u64 v[2:3], v[0:1], 0, v[32:33]
	global_store_short v[2:3], v5, off
	v_cvt_pk_bf16_f32 v2, v6, s0
	v_lshl_add_u64 v[0:1], v[0:1], 0, v[34:35]
	global_store_short v[0:1], v2, off offset:128
	v_and_b32_e32 v1, s5, v4
	v_lshlrev_b32_e32 v1, v37, v1
	v_lshlrev_b32_e32 v1, 2, v1
	v_or_b32_e32 v0, 17, v36
	v_lshlrev_b32_e32 v0, s26, v0
	v_add_u32_e32 v0, s27, v0
	v_ashrrev_i32_e32 v1, 31, v0
	v_lshlrev_b64 v[0:1], 10, v[0:1]
	v_lshl_add_u64 v[0:1], s[42:43], 0, v[0:1]
	v_add_u32_e32 v4, s55, v4
	v_mul_f32_e32 v5, v25, v233
	v_fmac_f32_e32 v5, v9, v217
	v_mul_f32_e32 v3, v9, v233
	v_fma_f32 v6, v25, v217, -v3
	v_cvt_pk_bf16_f32 v5, v5, s0
	v_lshl_add_u64 v[2:3], v[0:1], 0, v[32:33]
	global_store_short v[2:3], v5, off
	v_cvt_pk_bf16_f32 v2, v6, s0
	v_lshl_add_u64 v[0:1], v[0:1], 0, v[34:35]
	global_store_short v[0:1], v2, off offset:128
	v_and_b32_e32 v1, s5, v4
	v_lshlrev_b32_e32 v1, v37, v1
	v_lshlrev_b32_e32 v1, 2, v1
	v_or_b32_e32 v0, 18, v36
	v_lshlrev_b32_e32 v0, s26, v0
	v_add_u32_e32 v0, s27, v0
	v_ashrrev_i32_e32 v1, 31, v0
	v_lshlrev_b64 v[0:1], 10, v[0:1]
	v_lshl_add_u64 v[0:1], s[42:43], 0, v[0:1]
	v_add_u32_e32 v4, s55, v4
	v_mul_f32_e32 v5, v26, v234
	v_fmac_f32_e32 v5, v10, v218
	v_mul_f32_e32 v3, v10, v234
	v_fma_f32 v6, v26, v218, -v3
	v_cvt_pk_bf16_f32 v5, v5, s0
	v_lshl_add_u64 v[2:3], v[0:1], 0, v[32:33]
	global_store_short v[2:3], v5, off
	v_cvt_pk_bf16_f32 v2, v6, s0
	v_lshl_add_u64 v[0:1], v[0:1], 0, v[34:35]
	global_store_short v[0:1], v2, off offset:128
	v_and_b32_e32 v1, s5, v4
	v_lshlrev_b32_e32 v1, v37, v1
	v_lshlrev_b32_e32 v1, 2, v1
	v_or_b32_e32 v0, 19, v36
	v_lshlrev_b32_e32 v0, s26, v0
	v_add_u32_e32 v0, s27, v0
	v_ashrrev_i32_e32 v1, 31, v0
	v_lshlrev_b64 v[0:1], 10, v[0:1]
	v_lshl_add_u64 v[0:1], s[42:43], 0, v[0:1]
	v_add_u32_e32 v4, s14, v4
	s_mov_b64 s[14:15], 0
	v_mul_f32_e32 v5, v27, v235
	v_fmac_f32_e32 v5, v11, v219
	v_mul_f32_e32 v3, v11, v235
	v_fma_f32 v6, v27, v219, -v3
	v_cvt_pk_bf16_f32 v5, v5, s0
	v_lshl_add_u64 v[2:3], v[0:1], 0, v[32:33]
	global_store_short v[2:3], v5, off
	v_cvt_pk_bf16_f32 v2, v6, s0
	v_lshl_add_u64 v[0:1], v[0:1], 0, v[34:35]
	global_store_short v[0:1], v2, off offset:128
	v_and_b32_e32 v1, s5, v4
	v_lshlrev_b32_e32 v1, v37, v1
	v_lshlrev_b32_e32 v1, 2, v1
	v_or_b32_e32 v0, 24, v36
	v_lshlrev_b32_e32 v0, s26, v0
	v_add_u32_e32 v0, s27, v0
	v_ashrrev_i32_e32 v1, 31, v0
	v_lshlrev_b64 v[0:1], 10, v[0:1]
	v_lshl_add_u64 v[0:1], s[42:43], 0, v[0:1]
	v_add_u32_e32 v4, s55, v4
	v_mul_f32_e32 v5, v28, v236
	v_fmac_f32_e32 v5, v12, v220
	v_mul_f32_e32 v3, v12, v236
	v_fma_f32 v6, v28, v220, -v3
	v_cvt_pk_bf16_f32 v5, v5, s0
	v_lshl_add_u64 v[2:3], v[0:1], 0, v[32:33]
	global_store_short v[2:3], v5, off
	v_cvt_pk_bf16_f32 v2, v6, s0
	v_lshl_add_u64 v[0:1], v[0:1], 0, v[34:35]
	global_store_short v[0:1], v2, off offset:128
	v_and_b32_e32 v1, s5, v4
	v_lshlrev_b32_e32 v1, v37, v1
	v_lshlrev_b32_e32 v1, 2, v1
	v_or_b32_e32 v0, 25, v36
	v_lshlrev_b32_e32 v0, s26, v0
	v_add_u32_e32 v0, s27, v0
	v_ashrrev_i32_e32 v1, 31, v0
	v_lshlrev_b64 v[0:1], 10, v[0:1]
	v_lshl_add_u64 v[0:1], s[42:43], 0, v[0:1]
	v_add_u32_e32 v4, s55, v4
	v_mul_f32_e32 v5, v29, v237
	v_fmac_f32_e32 v5, v13, v221
	v_mul_f32_e32 v3, v13, v237
	v_fma_f32 v6, v29, v221, -v3
	v_cvt_pk_bf16_f32 v5, v5, s0
	v_lshl_add_u64 v[2:3], v[0:1], 0, v[32:33]
	global_store_short v[2:3], v5, off
	v_cvt_pk_bf16_f32 v2, v6, s0
	v_lshl_add_u64 v[0:1], v[0:1], 0, v[34:35]
	global_store_short v[0:1], v2, off offset:128
	v_and_b32_e32 v1, s5, v4
	v_lshlrev_b32_e32 v1, v37, v1
	v_lshlrev_b32_e32 v1, 2, v1
	v_or_b32_e32 v0, 26, v36
	v_lshlrev_b32_e32 v0, s26, v0
	v_add_u32_e32 v0, s27, v0
	v_ashrrev_i32_e32 v1, 31, v0
	v_lshlrev_b64 v[0:1], 10, v[0:1]
	v_lshl_add_u64 v[0:1], s[42:43], 0, v[0:1]
	v_mul_f32_e32 v5, v30, v238
	v_fmac_f32_e32 v5, v14, v222
	v_mul_f32_e32 v3, v14, v238
	v_fma_f32 v6, v30, v222, -v3
	v_cvt_pk_bf16_f32 v5, v5, s0
	v_lshl_add_u64 v[2:3], v[0:1], 0, v[32:33]
	global_store_short v[2:3], v5, off
	v_cvt_pk_bf16_f32 v2, v6, s0
	v_lshl_add_u64 v[0:1], v[0:1], 0, v[34:35]
	global_store_short v[0:1], v2, off offset:128
	v_add_u32_e32 v1, s55, v4
	v_and_b32_e32 v1, s5, v1
	v_lshlrev_b32_e32 v1, v37, v1
	v_lshlrev_b32_e32 v1, 2, v1
	v_or_b32_e32 v0, 27, v36
	v_lshlrev_b32_e32 v0, s26, v0
	v_add_u32_e32 v0, s27, v0
	v_ashrrev_i32_e32 v1, 31, v0
	v_lshlrev_b64 v[0:1], 10, v[0:1]
	v_lshl_add_u64 v[0:1], s[42:43], 0, v[0:1]
	v_mul_f32_e32 v4, v31, v239
	v_fmac_f32_e32 v4, v15, v223
	v_mul_f32_e32 v3, v15, v239
	v_fma_f32 v5, v31, v223, -v3
	v_cvt_pk_bf16_f32 v4, v4, s0
	v_lshl_add_u64 v[2:3], v[0:1], 0, v[32:33]
	global_store_short v[2:3], v4, off
	v_cvt_pk_bf16_f32 v2, v5, s0
	v_lshl_add_u64 v[0:1], v[0:1], 0, v[34:35]
	global_store_short v[0:1], v2, off offset:128
	s_barrier
